# v056 with the whole instruction stream shifted by 4 bytes (one s_nop 0 at entry): code placement check
# baseline (speedup 1.0000x reference)
; #define LAS __attribute__((address_space(3)))
; __device__ __forceinline__ unsigned xb_add(unsigned* p, unsigned v) { return __hip_atomic_fetch_add(p, v, __ATOMIC_RELAXED, __HIP_MEMORY_SCOPE_AGENT); }
; __device__ __forceinline__ unsigned xb_xcc_id() { return (unsigned)__builtin_amdgcn_s_getreg((3 << 11) | 20) & 0xFu; }
; __device__ __forceinline__ XcdBarrier xcd_barrier_post(unsigned* bar, volatile LAS unsigned* st) {
;     XcdBarrier b; b.bar = bar; b.x = xb_xcc_id(); b.st = st;
;     if (threadIdx.x == 0) (void)xb_add(&bar[XB_XCNT(b.x)], 1u);
;     return b;
; }
; __global__ void __launch_bounds__(NWAVES * 64, 2) enc_fwd(Args args) {
;     extern __shared__ __attribute__((aligned(16))) unsigned char lds_raw[];
;     LAS unsigned char* lds = (LAS unsigned char*)lds_raw;
;     volatile LAS unsigned* MISC = (volatile LAS unsigned*)(lds + MISC_OFF);
;     const int wid = __builtin_amdgcn_readfirstlane((int)threadIdx.x >> 6);
;     const int G = gridDim.x, bx = blockIdx.x;
;     const int gw = bx * NWAVES + wid, NGW = G * NWAVES;
;     ...
;     unsigned char* ws0 = args.ws;
;     for (int u = threadIdx.x; u < (LDS_BYTES - LDSCTL_OFF) / 4; u += NWAVES * 64) ((LAS unsigned*)(lds + LDSCTL_OFF))[u] = 0u;
;     __syncthreads();
;     XcdBarrier bar; bar.bar = (unsigned*)(ws0 + WS_CTL) + CW_BAR; bar.x = 0; bar.st = nullptr;
;     if (MK_ONE_LAUNCH) bar = xcd_barrier_post((unsigned*)(ws0 + WS_CTL) + CW_BAR, MISC + 8);
_Z7enc_fwd4Args:
	s_load_dword s68, s[0:1], 0x128
	s_nop 0
	s_mov_b32 s92, s2
	s_add_u32 s2, s0, 0x128
	s_addc_u32 s3, s1, 0
	v_lshl_add_u32 v1, v0, 2, 0
	v_writelane_b32 v249, s2, 0
	v_add_u32_e32 v1, 0x20000, v1
	v_mov_b32_e32 v2, 0
	v_readfirstlane_b32 s30, v0
	v_writelane_b32 v249, s3, 1
	ds_write2st64_b32 v1, v2, v2 offset1:8
	ds_write2st64_b32 v1, v2, v2 offset0:16 offset1:24
	v_or_b32_e32 v1, 0x800, v0
	s_mov_b64 s[4:5], -1
	s_and_saveexec_b64 s[6:7], s[4:5]
	v_lshl_add_u32 v3, v1, 2, 0
	v_add_u32_e32 v3, 0x20000, v3
	ds_write_b32 v3, v2
	s_or_b64 exec, exec, s[6:7]
	s_and_saveexec_b64 s[6:7], s[4:5]
	s_add_i32 s4, 0, 0x20000
	v_lshl_add_u32 v1, v1, 2, s4
	v_mov_b32_e32 v2, 0
	ds_write_b32 v1, v2 offset:2048
	s_or_b64 exec, exec, s[6:7]
	v_or_b32_e32 v1, 0xc00, v0
	v_cmp_gt_u32_e64 s[4:5], 7, 6
	v_cmp_gt_u32_e64 s[8:9], 7, 5
	s_and_saveexec_b64 s[6:7], s[8:9]
	v_lshl_add_u32 v2, v1, 2, 0
	v_add_u32_e32 v2, 0x20000, v2
	v_mov_b32_e32 v3, 0
	ds_write_b32 v2, v3
	s_or_b64 exec, exec, s[6:7]
	s_load_dwordx2 s[90:91], s[0:1], 0x120
	s_load_dwordx8 s[60:67], s[0:1], 0x100
	s_and_saveexec_b64 s[6:7], s[4:5]
	s_add_i32 s4, 0, 0x20000
	v_lshl_add_u32 v1, v1, 2, s4
	v_mov_b32_e32 v2, 0
	ds_write_b32 v1, v2 offset:2048
	s_or_b64 exec, exec, s[6:7]
	s_load_dwordx16 s[4:19], s[0:1], 0x0
	s_waitcnt lgkmcnt(0)
	s_barrier
	v_cmp_eq_u32_e64 s[20:21], 0, v0
	v_writelane_b32 v249, s4, 2
	s_nop 1
	v_writelane_b32 v249, s5, 3
	v_writelane_b32 v249, s6, 4
	v_writelane_b32 v249, s7, 5
	v_writelane_b32 v249, s8, 6
	v_writelane_b32 v249, s9, 7
	v_writelane_b32 v249, s10, 8
	v_writelane_b32 v249, s11, 9
	v_writelane_b32 v249, s12, 10
	v_writelane_b32 v249, s13, 11
	v_writelane_b32 v249, s14, 12
	v_writelane_b32 v249, s15, 13
	v_writelane_b32 v249, s16, 14
	v_writelane_b32 v249, s17, 15
	v_writelane_b32 v249, s18, 16
	v_writelane_b32 v249, s19, 17
	s_load_dwordx16 s[4:19], s[0:1], 0x40
	s_waitcnt lgkmcnt(0)
	v_writelane_b32 v249, s4, 18
	s_nop 1
	v_writelane_b32 v249, s5, 19
	v_writelane_b32 v249, s6, 20
	v_writelane_b32 v249, s7, 21
	v_writelane_b32 v249, s8, 22
	v_writelane_b32 v249, s9, 23
	v_writelane_b32 v249, s10, 24
	v_writelane_b32 v249, s11, 25
	v_writelane_b32 v249, s12, 26
	v_writelane_b32 v249, s13, 27
	v_writelane_b32 v249, s14, 28
	v_writelane_b32 v249, s15, 29
	v_writelane_b32 v249, s16, 30
	v_writelane_b32 v249, s17, 31
	v_writelane_b32 v249, s18, 32
	v_writelane_b32 v249, s19, 33
	s_load_dwordx16 s[4:19], s[0:1], 0x80
	s_waitcnt lgkmcnt(0)
	v_writelane_b32 v249, s4, 34
	s_nop 1
	v_writelane_b32 v249, s5, 35
	v_writelane_b32 v249, s6, 36
	v_writelane_b32 v249, s7, 37
	v_writelane_b32 v249, s8, 38
	v_writelane_b32 v249, s9, 39
	v_writelane_b32 v249, s10, 40
	v_writelane_b32 v249, s11, 41
	v_writelane_b32 v249, s12, 42
	v_writelane_b32 v249, s13, 43
	v_writelane_b32 v249, s14, 44
	v_writelane_b32 v249, s15, 45
	v_writelane_b32 v249, s16, 46
	v_writelane_b32 v249, s17, 47
	v_writelane_b32 v249, s18, 48
	v_writelane_b32 v249, s19, 49
	s_load_dwordx16 s[4:19], s[0:1], 0xc0
	s_add_u32 s0, s66, 0x4000
	s_addc_u32 s1, s67, 0
	s_waitcnt lgkmcnt(0)
	v_writelane_b32 v249, s4, 50
	s_nop 1
	v_writelane_b32 v249, s5, 51
	v_writelane_b32 v249, s6, 52
	v_writelane_b32 v249, s7, 53
	v_writelane_b32 v249, s8, 54
	v_writelane_b32 v249, s9, 55
	v_writelane_b32 v249, s10, 56
	v_writelane_b32 v249, s11, 57
	v_writelane_b32 v249, s12, 58
	v_writelane_b32 v249, s13, 59
	v_writelane_b32 v249, s14, 60
	v_writelane_b32 v250, s18, 0
	v_writelane_b32 v249, s15, 61
	v_writelane_b32 v250, s19, 1
	s_getreg_b32 s4, hwreg(HW_REG_XCC_ID, 0, 4)
	v_writelane_b32 v249, s16, 62
	s_and_b32 s8, s4, 15
	v_writelane_b32 v249, s17, 63
	s_lshl_b32 s9, s8, 6
	s_and_saveexec_b64 s[4:5], s[20:21]
	s_cbranch_execz .LBB0_11
	s_mov_b64 s[6:7], exec
	v_mbcnt_lo_u32_b32 v1, s6, 0
	v_mbcnt_hi_u32_b32 v1, s7, v1
	v_cmp_eq_u32_e32 vcc, 0, v1
	s_and_b64 s[10:11], exec, vcc
	s_mov_b64 exec, s[10:11]
	s_cbranch_execz .LBB0_11
	s_lshl_b32 s10, s9, 2
	s_bcnt1_i32_b64 s6, s[6:7]
	v_mov_b32_e32 v1, s10
	v_mov_b32_e32 v2, s6
	global_atomic_add v1, v2, s[0:1] offset:1024
